# e25: nt on the staggered gla_finish's full-line Y1 stores in P10, so the overlapping FNet GEMM keeps its operand panels in L2 (on top of e22)
# speedup vs baseline: 1.0059x; 1.0037x over previous
.LBB0_1595:
	s_add_i32 s0, s34, s37
	s_ashr_i32 s1, s0, 31
	s_lshr_b32 s1, s1, 19
	s_add_i32 s1, s0, s1
	s_ashr_i32 s4, s1, 13
	s_and_b32 s1, s1, 0xffffe000
	s_sub_i32 s0, s0, s1
	s_mul_hi_i32 s5, s4, 0x2100
	s_mulk_i32 s4, 0x2100
	s_ashr_i32 s1, s0, 31
	s_add_u32 s0, s4, s0
	s_addc_u32 s1, s5, s1
	s_mul_hi_u32 s4, s0, 0xc00
	s_mul_i32 s5, s0, 0xc00
	s_mul_i32 s6, s1, 0xc00
	s_lshl_b64 s[0:1], s[0:1], 13
	s_add_i32 s4, s4, s6
	v_lshl_add_u64 v[12:13], v[52:53], 0, s[0:1]
	v_or_b32_e32 v10, s5, v50
	v_mov_b32_e32 v11, s4
	v_add_co_u32_e32 v36, vcc, s35, v12
	v_lshlrev_b64 v[34:35], 1, v[10:11]
	s_nop 0
	v_addc_co_u32_e32 v37, vcc, 0, v13, vcc
	global_load_dwordx4 v[30:33], v[12:13], off nt
	global_load_dwordx4 v[26:29], v[12:13], off offset:1024 nt
	global_load_dwordx4 v[22:25], v[12:13], off offset:2048 nt
	global_load_dwordx4 v[18:21], v[12:13], off offset:3072 nt
	global_load_dwordx4 v[14:17], v[36:37], off nt
	s_nop 0
	global_load_dwordx4 v[10:13], v[36:37], off offset:1024 nt
	v_lshl_add_u64 v[36:37], s[20:21], 0, v[34:35]
	v_lshl_add_u64 v[38:39], s[22:23], 0, v[34:35]
	v_lshl_add_u64 v[40:41], s[24:25], 0, v[34:35]
	v_lshl_add_u64 v[42:43], s[26:27], 0, v[34:35]
	global_load_dwordx4 v[56:59], v[36:37], off nt
	global_load_dwordx4 v[60:63], v[36:37], off offset:2048 nt
	global_load_dwordx4 v[118:121], v[40:41], off nt
	global_load_dwordx4 v[122:125], v[40:41], off offset:2048 nt
	global_load_dwordx4 v[126:129], v[38:39], off nt
	global_load_dwordx4 v[132:135], v[36:37], off offset:3072 nt
	global_load_dwordx4 v[136:139], v[38:39], off offset:2048 nt
	global_load_dwordx4 v[140:143], v[38:39], off offset:3072 nt
	global_load_dwordx4 v[144:147], v[42:43], off nt
	global_load_dwordx4 v[148:151], v[40:41], off offset:3072 nt
	global_load_dwordx4 v[152:155], v[42:43], off offset:2048 nt
	global_load_dwordx4 v[156:159], v[42:43], off offset:3072 nt
	v_add_co_u32_e32 v36, vcc, s35, v36
	s_add_u32 s28, s30, s0
	s_nop 0
	v_addc_co_u32_e32 v37, vcc, 0, v37, vcc
	v_add_co_u32_e32 v38, vcc, s35, v38
	v_lshlrev_b32_e32 v130, 1, v50
	s_nop 0
	v_addc_co_u32_e32 v39, vcc, 0, v39, vcc
	v_add_co_u32_e32 v72, vcc, s35, v40
	s_addc_u32 s29, s31, s1
	s_nop 0
	v_addc_co_u32_e32 v73, vcc, 0, v41, vcc
	v_add_co_u32_e32 v74, vcc, s35, v42
	v_or_b32_e32 v34, 0x400, v34
	v_lshl_add_u64 v[44:45], s[28:29], 0, v[130:131]
	v_addc_co_u32_e32 v75, vcc, 0, v43, vcc
	v_lshl_add_u64 v[46:47], s[20:21], 0, v[34:35]
	v_lshl_add_u64 v[48:49], s[22:23], 0, v[34:35]
	v_lshl_add_u64 v[70:71], s[24:25], 0, v[34:35]
	v_lshl_add_u64 v[34:35], s[26:27], 0, v[34:35]
	v_add_co_u32_e32 v54, vcc, s35, v44
	s_add_i32 s0, s37, 8
	s_nop 0
	v_addc_co_u32_e32 v55, vcc, 0, v45, vcc
	global_load_dwordx4 v[164:167], v[46:47], off nt
	global_load_dwordx4 v[168:171], v[48:49], off nt
	global_load_dwordx4 v[172:175], v[70:71], off nt
	global_load_dwordx4 v[176:179], v[34:35], off nt
	global_load_dwordx4 v[180:183], v[36:37], off nt
	s_nop 0
	global_load_dwordx4 v[34:37], v[36:37], off offset:1024 nt
	s_nop 0
	global_load_dwordx4 v[184:187], v[38:39], off nt
	s_nop 0
	global_load_dwordx4 v[38:41], v[38:39], off offset:1024 nt
	s_nop 0
	global_load_dwordx4 v[188:191], v[72:73], off nt
	global_load_dwordx4 v[42:45], v[72:73], off offset:1024 nt
	global_load_dwordx4 v[192:195], v[74:75], off nt
	global_load_dwordx4 v[46:49], v[74:75], off offset:1024 nt
	s_cmp_lt_u32 s37, 56
	s_mov_b32 s37, s0
	s_waitcnt vmcnt(0)
	v_lshlrev_b32_e32 v160, 16, v62
	v_and_b32_e32 v161, 0xffff0000, v62
	v_lshlrev_b32_e32 v110, 16, v30
	v_and_b32_e32 v111, 0xffff0000, v30
	v_lshlrev_b32_e32 v78, 16, v14
	v_and_b32_e32 v79, 0xffff0000, v14
	v_lshlrev_b32_e32 v80, 16, v15
	v_and_b32_e32 v81, 0xffff0000, v15
	v_lshlrev_b32_e32 v82, 16, v16
	v_and_b32_e32 v83, 0xffff0000, v16
	v_lshlrev_b32_e32 v84, 16, v17
	v_and_b32_e32 v85, 0xffff0000, v17
	v_lshlrev_b32_e32 v70, 16, v10
	v_and_b32_e32 v71, 0xffff0000, v10
	v_lshlrev_b32_e32 v72, 16, v11
	v_and_b32_e32 v73, 0xffff0000, v11
	v_lshlrev_b32_e32 v74, 16, v12
	v_and_b32_e32 v75, 0xffff0000, v12
	v_lshlrev_b32_e32 v76, 16, v13
	v_and_b32_e32 v77, 0xffff0000, v13
	v_lshlrev_b32_e32 v10, 16, v56
	v_and_b32_e32 v11, 0xffff0000, v56
	v_lshlrev_b32_e32 v12, 16, v126
	v_and_b32_e32 v13, 0xffff0000, v126
	v_lshlrev_b32_e32 v14, 16, v118
	v_and_b32_e32 v15, 0xffff0000, v118
	v_lshlrev_b32_e32 v16, 16, v144
	v_and_b32_e32 v17, 0xffff0000, v144
	v_lshlrev_b32_e32 v112, 16, v31
	v_and_b32_e32 v113, 0xffff0000, v31
	v_lshlrev_b32_e32 v114, 16, v32
	v_and_b32_e32 v115, 0xffff0000, v32
	v_lshlrev_b32_e32 v116, 16, v33
	v_and_b32_e32 v117, 0xffff0000, v33
	v_lshlrev_b32_e32 v102, 16, v26
	v_and_b32_e32 v103, 0xffff0000, v26
	v_lshlrev_b32_e32 v104, 16, v27
	v_and_b32_e32 v105, 0xffff0000, v27
	v_lshlrev_b32_e32 v106, 16, v28
	v_and_b32_e32 v107, 0xffff0000, v28
	v_lshlrev_b32_e32 v108, 16, v29
	v_and_b32_e32 v109, 0xffff0000, v29
	v_lshlrev_b32_e32 v94, 16, v22
	v_and_b32_e32 v95, 0xffff0000, v22
	v_lshlrev_b32_e32 v96, 16, v23
	v_and_b32_e32 v97, 0xffff0000, v23
	v_lshlrev_b32_e32 v98, 16, v24
	v_and_b32_e32 v99, 0xffff0000, v24
	v_lshlrev_b32_e32 v100, 16, v25
	v_and_b32_e32 v101, 0xffff0000, v25
	v_lshlrev_b32_e32 v86, 16, v18
	v_and_b32_e32 v87, 0xffff0000, v18
	v_lshlrev_b32_e32 v88, 16, v19
	v_and_b32_e32 v89, 0xffff0000, v19
	v_lshlrev_b32_e32 v90, 16, v20
	v_and_b32_e32 v91, 0xffff0000, v20
	v_lshlrev_b32_e32 v92, 16, v21
	v_and_b32_e32 v93, 0xffff0000, v21
	v_lshlrev_b32_e32 v18, 16, v57
	v_and_b32_e32 v19, 0xffff0000, v57
	v_lshlrev_b32_e32 v20, 16, v127
	v_and_b32_e32 v21, 0xffff0000, v127
	v_lshlrev_b32_e32 v22, 16, v119
	v_and_b32_e32 v23, 0xffff0000, v119
	v_lshlrev_b32_e32 v24, 16, v145
	v_and_b32_e32 v25, 0xffff0000, v145
	v_lshlrev_b32_e32 v26, 16, v58
	v_and_b32_e32 v27, 0xffff0000, v58
	v_lshlrev_b32_e32 v28, 16, v128
	v_and_b32_e32 v29, 0xffff0000, v128
	v_lshlrev_b32_e32 v30, 16, v120
	v_and_b32_e32 v31, 0xffff0000, v120
	v_lshlrev_b32_e32 v32, 16, v146
	v_and_b32_e32 v33, 0xffff0000, v146
	v_lshlrev_b32_e32 v56, 16, v59
	v_and_b32_e32 v57, 0xffff0000, v59
	v_lshlrev_b32_e32 v58, 16, v129
	v_and_b32_e32 v59, 0xffff0000, v129
	v_lshlrev_b32_e32 v118, 16, v121
	v_and_b32_e32 v119, 0xffff0000, v121
	v_lshlrev_b32_e32 v120, 16, v147
	v_and_b32_e32 v121, 0xffff0000, v147
	v_lshlrev_b32_e32 v126, 16, v60
	v_and_b32_e32 v127, 0xffff0000, v60
	v_lshlrev_b32_e32 v128, 16, v136
	v_and_b32_e32 v129, 0xffff0000, v136
	v_lshlrev_b32_e32 v144, 16, v122
	v_and_b32_e32 v145, 0xffff0000, v122
	v_lshlrev_b32_e32 v146, 16, v152
	v_and_b32_e32 v147, 0xffff0000, v152
	v_lshlrev_b32_e32 v60, 16, v61
	v_and_b32_e32 v61, 0xffff0000, v61
	v_lshlrev_b32_e32 v136, 16, v137
	v_and_b32_e32 v137, 0xffff0000, v137
	v_lshlrev_b32_e32 v122, 16, v123
	v_and_b32_e32 v123, 0xffff0000, v123
	v_lshlrev_b32_e32 v152, 16, v153
	v_and_b32_e32 v153, 0xffff0000, v153
	v_lshlrev_b32_e32 v196, 16, v138
	v_and_b32_e32 v197, 0xffff0000, v138
	v_lshlrev_b32_e32 v198, 16, v124
	v_and_b32_e32 v199, 0xffff0000, v124
	v_lshlrev_b32_e32 v200, 16, v154
	v_and_b32_e32 v201, 0xffff0000, v154
	v_lshlrev_b32_e32 v62, 16, v63
	v_and_b32_e32 v63, 0xffff0000, v63
	v_lshlrev_b32_e32 v138, 16, v139
	v_and_b32_e32 v139, 0xffff0000, v139
	v_lshlrev_b32_e32 v124, 16, v125
	v_and_b32_e32 v125, 0xffff0000, v125
	v_lshlrev_b32_e32 v154, 16, v155
	v_and_b32_e32 v155, 0xffff0000, v155
	v_lshlrev_b32_e32 v202, 16, v132
	v_and_b32_e32 v203, 0xffff0000, v132
	v_lshlrev_b32_e32 v204, 16, v140
	v_and_b32_e32 v205, 0xffff0000, v140
	v_lshlrev_b32_e32 v206, 16, v148
	v_and_b32_e32 v207, 0xffff0000, v148
	v_lshlrev_b32_e32 v208, 16, v156
	v_and_b32_e32 v209, 0xffff0000, v156
	v_lshlrev_b32_e32 v132, 16, v133
	v_and_b32_e32 v133, 0xffff0000, v133
	v_lshlrev_b32_e32 v140, 16, v141
	v_and_b32_e32 v141, 0xffff0000, v141
	v_lshlrev_b32_e32 v148, 16, v149
	v_and_b32_e32 v149, 0xffff0000, v149
	v_lshlrev_b32_e32 v156, 16, v157
	v_and_b32_e32 v157, 0xffff0000, v157
	v_lshlrev_b32_e32 v210, 16, v134
	v_and_b32_e32 v211, 0xffff0000, v134
	v_lshlrev_b32_e32 v212, 16, v142
	v_and_b32_e32 v213, 0xffff0000, v142
	v_lshlrev_b32_e32 v214, 16, v150
	v_and_b32_e32 v215, 0xffff0000, v150
	v_lshlrev_b32_e32 v216, 16, v158
	v_and_b32_e32 v217, 0xffff0000, v158
	v_lshlrev_b32_e32 v134, 16, v135
	v_and_b32_e32 v135, 0xffff0000, v135
	v_lshlrev_b32_e32 v142, 16, v143
	v_and_b32_e32 v143, 0xffff0000, v143
	v_lshlrev_b32_e32 v150, 16, v151
	v_and_b32_e32 v151, 0xffff0000, v151
	v_lshlrev_b32_e32 v158, 16, v159
	v_and_b32_e32 v159, 0xffff0000, v159
	v_pk_add_f32 v[10:11], v[10:11], v[12:13]
	v_pk_add_f32 v[12:13], v[14:15], v[16:17]
	v_pk_add_f32 v[14:15], v[18:19], v[20:21]
	v_pk_add_f32 v[16:17], v[22:23], v[24:25]
	v_pk_add_f32 v[18:19], v[26:27], v[28:29]
	v_pk_add_f32 v[20:21], v[30:31], v[32:33]
	v_pk_add_f32 v[22:23], v[56:57], v[58:59]
	v_pk_add_f32 v[24:25], v[118:119], v[120:121]
	v_lshlrev_b32_e32 v26, 16, v164
	v_and_b32_e32 v27, 0xffff0000, v164
	v_lshlrev_b32_e32 v28, 16, v168
	v_and_b32_e32 v29, 0xffff0000, v168
	v_lshlrev_b32_e32 v30, 16, v172
	v_and_b32_e32 v31, 0xffff0000, v172
	v_lshlrev_b32_e32 v32, 16, v176
	v_and_b32_e32 v33, 0xffff0000, v176
	v_lshlrev_b32_e32 v56, 16, v165
	v_and_b32_e32 v57, 0xffff0000, v165
	v_lshlrev_b32_e32 v58, 16, v169
	v_and_b32_e32 v59, 0xffff0000, v169
	v_lshlrev_b32_e32 v118, 16, v173
	v_and_b32_e32 v119, 0xffff0000, v173
	v_lshlrev_b32_e32 v120, 16, v177
	v_and_b32_e32 v121, 0xffff0000, v177
	v_lshlrev_b32_e32 v164, 16, v166
	v_and_b32_e32 v165, 0xffff0000, v166
	v_lshlrev_b32_e32 v168, 16, v170
	v_and_b32_e32 v169, 0xffff0000, v170
	v_lshlrev_b32_e32 v172, 16, v174
	v_and_b32_e32 v173, 0xffff0000, v174
	v_lshlrev_b32_e32 v176, 16, v178
	v_and_b32_e32 v177, 0xffff0000, v178
	v_pk_add_f32 v[126:127], v[126:127], v[128:129]
	v_pk_add_f32 v[128:129], v[144:145], v[146:147]
	v_pk_add_f32 v[60:61], v[60:61], v[136:137]
	v_pk_add_f32 v[122:123], v[122:123], v[152:153]
	v_pk_add_f32 v[136:137], v[160:161], v[196:197]
	v_pk_add_f32 v[144:145], v[198:199], v[200:201]
	v_pk_add_f32 v[62:63], v[62:63], v[138:139]
	v_pk_add_f32 v[124:125], v[124:125], v[154:155]
	v_pk_add_f32 v[138:139], v[202:203], v[204:205]
	v_pk_add_f32 v[146:147], v[206:207], v[208:209]
	v_pk_add_f32 v[132:133], v[132:133], v[140:141]
	v_pk_add_f32 v[140:141], v[148:149], v[156:157]
	v_pk_add_f32 v[148:149], v[210:211], v[212:213]
	v_pk_add_f32 v[152:153], v[214:215], v[216:217]
	v_pk_add_f32 v[134:135], v[134:135], v[142:143]
	v_pk_add_f32 v[142:143], v[150:151], v[158:159]
	v_lshlrev_b32_e32 v150, 16, v180
	v_and_b32_e32 v151, 0xffff0000, v180
	v_lshlrev_b32_e32 v154, 16, v184
	v_and_b32_e32 v155, 0xffff0000, v184
	v_lshlrev_b32_e32 v156, 16, v188
	v_and_b32_e32 v157, 0xffff0000, v188
	v_lshlrev_b32_e32 v158, 16, v192
	v_and_b32_e32 v159, 0xffff0000, v192
	v_lshlrev_b32_e32 v202, 16, v34
	v_and_b32_e32 v203, 0xffff0000, v34
	v_lshlrev_b32_e32 v204, 16, v38
	v_and_b32_e32 v205, 0xffff0000, v38
	v_lshlrev_b32_e32 v206, 16, v42
	v_and_b32_e32 v207, 0xffff0000, v42
	v_lshlrev_b32_e32 v208, 16, v46
	v_and_b32_e32 v209, 0xffff0000, v46
	v_lshlrev_b32_e32 v214, 16, v43
	v_and_b32_e32 v215, 0xffff0000, v43
	v_lshlrev_b32_e32 v218, 16, v36
	v_and_b32_e32 v219, 0xffff0000, v36
	v_lshlrev_b32_e32 v220, 16, v40
	v_and_b32_e32 v221, 0xffff0000, v40
	v_lshlrev_b32_e32 v222, 16, v44
	v_and_b32_e32 v223, 0xffff0000, v44
	v_lshlrev_b32_e32 v224, 16, v48
	v_and_b32_e32 v225, 0xffff0000, v48
	v_pk_add_f32 v[42:43], v[10:11], v[12:13]
	v_lshlrev_b32_e32 v166, 16, v167
	v_and_b32_e32 v167, 0xffff0000, v167
	v_lshlrev_b32_e32 v170, 16, v171
	v_and_b32_e32 v171, 0xffff0000, v171
	v_lshlrev_b32_e32 v174, 16, v175
	v_and_b32_e32 v175, 0xffff0000, v175
	v_lshlrev_b32_e32 v178, 16, v179
	v_and_b32_e32 v179, 0xffff0000, v179
	v_lshlrev_b32_e32 v160, 16, v181
	v_and_b32_e32 v161, 0xffff0000, v181
	v_lshlrev_b32_e32 v180, 16, v185
	v_and_b32_e32 v181, 0xffff0000, v185
	v_lshlrev_b32_e32 v184, 16, v189
	v_and_b32_e32 v185, 0xffff0000, v189
	v_lshlrev_b32_e32 v188, 16, v193
	v_and_b32_e32 v189, 0xffff0000, v193
	v_lshlrev_b32_e32 v192, 16, v182
	v_and_b32_e32 v193, 0xffff0000, v182
	v_lshlrev_b32_e32 v196, 16, v186
	v_and_b32_e32 v197, 0xffff0000, v186
	v_lshlrev_b32_e32 v198, 16, v190
	v_and_b32_e32 v199, 0xffff0000, v190
	v_lshlrev_b32_e32 v200, 16, v194
	v_and_b32_e32 v201, 0xffff0000, v194
	v_lshlrev_b32_e32 v210, 16, v35
	v_and_b32_e32 v211, 0xffff0000, v35
	v_lshlrev_b32_e32 v212, 16, v39
	v_and_b32_e32 v213, 0xffff0000, v39
	v_lshlrev_b32_e32 v216, 16, v47
	v_and_b32_e32 v217, 0xffff0000, v47
	v_lshlrev_b32_e32 v230, 16, v45
	v_and_b32_e32 v231, 0xffff0000, v45
	v_lshlrev_b32_e32 v232, 16, v49
	v_and_b32_e32 v233, 0xffff0000, v49
	v_pk_add_f32 v[44:45], v[14:15], v[16:17]
	v_pk_add_f32 v[46:47], v[18:19], v[20:21]
	v_pk_add_f32 v[48:49], v[22:23], v[24:25]
	v_pk_add_f32 v[10:11], v[26:27], v[28:29]
	v_pk_add_f32 v[12:13], v[30:31], v[32:33]
	v_pk_add_f32 v[14:15], v[56:57], v[58:59]
	v_pk_add_f32 v[16:17], v[118:119], v[120:121]
	v_pk_add_f32 v[26:27], v[164:165], v[168:169]
	v_pk_add_f32 v[28:29], v[172:173], v[176:177]
	v_pk_add_f32 v[34:35], v[126:127], v[128:129]
	v_pk_add_f32 v[38:39], v[136:137], v[144:145]
	v_pk_add_f32 v[18:19], v[138:139], v[146:147]
	v_pk_add_f32 v[22:23], v[148:149], v[152:153]
	v_pk_add_f32 v[118:119], v[150:151], v[154:155]
	v_pk_add_f32 v[120:121], v[156:157], v[158:159]
	v_pk_add_f32 v[136:137], v[202:203], v[204:205]
	v_pk_add_f32 v[138:139], v[206:207], v[208:209]
	v_pk_add_f32 v[144:145], v[218:219], v[220:221]
	v_pk_add_f32 v[146:147], v[222:223], v[224:225]
	v_pk_mul_f32 v[152:153], v[42:43], v[42:43]
	v_lshlrev_b32_e32 v226, 16, v37
	v_and_b32_e32 v227, 0xffff0000, v37
	v_lshlrev_b32_e32 v228, 16, v41
	v_and_b32_e32 v229, 0xffff0000, v41
	v_pk_add_f32 v[30:31], v[166:167], v[170:171]
	v_pk_add_f32 v[32:33], v[174:175], v[178:179]
	v_pk_add_f32 v[36:37], v[60:61], v[122:123]
	v_pk_add_f32 v[40:41], v[62:63], v[124:125]
	v_pk_add_f32 v[20:21], v[132:133], v[140:141]
	v_pk_add_f32 v[24:25], v[134:135], v[142:143]
	v_pk_add_f32 v[122:123], v[160:161], v[180:181]
	v_pk_add_f32 v[124:125], v[184:185], v[188:189]
	v_pk_add_f32 v[126:127], v[192:193], v[196:197]
	v_pk_add_f32 v[128:129], v[198:199], v[200:201]
	v_pk_add_f32 v[140:141], v[210:211], v[212:213]
	v_pk_add_f32 v[142:143], v[214:215], v[216:217]
	v_pk_mul_f32 v[154:155], v[44:45], v[44:45]
	v_pk_add_f32 v[56:57], v[10:11], v[12:13]
	v_pk_add_f32 v[58:59], v[14:15], v[16:17]
	v_pk_add_f32 v[60:61], v[26:27], v[28:29]
	v_pk_mul_f32 v[160:161], v[34:35], v[34:35]
	v_pk_mul_f32 v[170:171], v[18:19], v[18:19]
	v_pk_add_f32 v[26:27], v[118:119], v[120:121]
	v_pk_add_f32 v[10:11], v[136:137], v[138:139]
	v_pk_add_f32 v[14:15], v[144:145], v[146:147]
	v_add_f32_e32 v144, v152, v153
	v_pk_add_f32 v[62:63], v[30:31], v[32:33]
	v_pk_mul_f32 v[164:165], v[36:37], v[36:37]
	v_pk_mul_f32 v[172:173], v[20:21], v[20:21]
	v_pk_add_f32 v[28:29], v[122:123], v[124:125]
	v_pk_add_f32 v[30:31], v[126:127], v[128:129]
	v_pk_add_f32 v[12:13], v[140:141], v[142:143]
	v_pk_mul_f32 v[118:119], v[56:57], v[56:57]
	v_add_f32_e32 v145, v160, v161
	v_add_f32_e32 v146, v170, v171
	v_pk_mul_f32 v[126:127], v[26:27], v[26:27]
	v_pk_mul_f32 v[136:137], v[10:11], v[10:11]
	v_add_f32_e32 v144, v154, v144
	v_pk_mul_f32 v[156:157], v[46:47], v[46:47]
	v_pk_mul_f32 v[120:121], v[58:59], v[58:59]
	v_pk_mul_f32 v[128:129], v[28:29], v[28:29]
	v_pk_mul_f32 v[138:139], v[12:13], v[12:13]
	v_add_f32_e32 v118, v118, v119
	v_add_f32_e32 v119, v164, v145
	v_add_f32_e32 v145, v172, v146
	v_add_f32_e32 v126, v126, v127
	v_add_f32_e32 v127, v136, v137
	v_add_f32_e32 v136, v155, v144
	v_lshlrev_b32_e32 v182, 16, v183
	v_and_b32_e32 v183, 0xffff0000, v183
	v_lshlrev_b32_e32 v186, 16, v187
	v_and_b32_e32 v187, 0xffff0000, v187
	v_lshlrev_b32_e32 v190, 16, v191
	v_and_b32_e32 v191, 0xffff0000, v191
	v_lshlrev_b32_e32 v194, 16, v195
	v_and_b32_e32 v195, 0xffff0000, v195
	v_pk_mul_f32 v[166:167], v[38:39], v[38:39]
	v_pk_mul_f32 v[174:175], v[22:23], v[22:23]
	v_add_f32_e32 v118, v120, v118
	v_add_f32_e32 v119, v165, v119
	v_add_f32_e32 v120, v173, v145
	v_add_f32_e32 v126, v128, v126
	v_add_f32_e32 v127, v138, v127
	v_add_f32_e32 v128, v156, v136
	v_pk_add_f32 v[132:133], v[182:183], v[186:187]
	v_pk_add_f32 v[134:135], v[190:191], v[194:195]
	v_pk_mul_f32 v[158:159], v[48:49], v[48:49]
	v_pk_mul_f32 v[122:123], v[60:61], v[60:61]
	v_pk_mul_f32 v[140:141], v[14:15], v[14:15]
	v_add_f32_e32 v118, v121, v118
	v_add_f32_e32 v119, v166, v119
	v_add_f32_e32 v120, v174, v120
	v_add_f32_e32 v121, v129, v126
	v_add_f32_e32 v126, v139, v127
	v_add_f32_e32 v127, v157, v128
	v_pk_add_f32 v[148:149], v[226:227], v[228:229]
	v_pk_add_f32 v[150:151], v[230:231], v[232:233]
	v_pk_mul_f32 v[168:169], v[40:41], v[40:41]
	v_pk_mul_f32 v[176:177], v[24:25], v[24:25]
	v_pk_add_f32 v[32:33], v[132:133], v[134:135]
	v_pk_mul_f32 v[132:133], v[30:31], v[30:31]
	v_add_f32_e32 v118, v122, v118
	v_add_f32_e32 v119, v167, v119
	v_add_f32_e32 v120, v175, v120
	v_add_f32_e32 v122, v140, v126
	v_add_f32_e32 v126, v158, v127
	v_pk_add_f32 v[16:17], v[148:149], v[150:151]
	v_pk_mul_f32 v[124:125], v[62:63], v[62:63]
	v_add_f32_e32 v121, v132, v121
	v_add_f32_e32 v118, v123, v118
	v_add_f32_e32 v119, v168, v119
	v_add_f32_e32 v120, v176, v120
	v_add_f32_e32 v123, v159, v126
	v_pk_mul_f32 v[134:135], v[32:33], v[32:33]
	v_pk_mul_f32 v[142:143], v[16:17], v[16:17]
	v_add_f32_e32 v121, v133, v121
	v_add_f32_e32 v122, v141, v122
	v_add_f32_e32 v118, v124, v118
	v_add_f32_e32 v119, v169, v119
	v_add_f32_e32 v120, v177, v120
	ds_bpermute_b32 v124, v1, v123
	v_add_f32_e32 v121, v134, v121
	v_add_f32_e32 v122, v142, v122
	v_add_f32_e32 v118, v125, v118
	ds_bpermute_b32 v125, v1, v119
	ds_bpermute_b32 v126, v1, v120
	v_add_f32_e32 v121, v135, v121
	v_add_f32_e32 v122, v143, v122
	ds_bpermute_b32 v127, v1, v118
	ds_bpermute_b32 v128, v1, v121
	ds_bpermute_b32 v129, v1, v122
	s_waitcnt lgkmcnt(5)
	v_add_f32_e32 v123, v123, v124
	s_waitcnt lgkmcnt(4)
	v_add_f32_e32 v119, v119, v125
	s_waitcnt lgkmcnt(3)
	v_add_f32_e32 v120, v120, v126
	ds_bpermute_b32 v124, v51, v123
	s_waitcnt lgkmcnt(3)
	v_add_f32_e32 v118, v118, v127
	ds_bpermute_b32 v125, v51, v119
	ds_bpermute_b32 v126, v51, v120
	s_waitcnt lgkmcnt(4)
	v_add_f32_e32 v121, v121, v128
	s_waitcnt lgkmcnt(3)
	v_add_f32_e32 v122, v122, v129
	ds_bpermute_b32 v127, v51, v118
	ds_bpermute_b32 v128, v51, v121
	ds_bpermute_b32 v129, v51, v122
	s_waitcnt lgkmcnt(5)
	v_add_f32_e32 v123, v123, v124
	s_waitcnt lgkmcnt(4)
	v_add_f32_e32 v119, v119, v125
	s_waitcnt lgkmcnt(3)
	v_add_f32_e32 v120, v120, v126
	ds_bpermute_b32 v124, v64, v123
	s_waitcnt lgkmcnt(3)
	v_add_f32_e32 v118, v118, v127
	ds_bpermute_b32 v125, v64, v119
	ds_bpermute_b32 v126, v64, v120
	s_waitcnt lgkmcnt(4)
	v_add_f32_e32 v121, v121, v128
	s_waitcnt lgkmcnt(3)
	v_add_f32_e32 v122, v122, v129
	ds_bpermute_b32 v127, v64, v118
	ds_bpermute_b32 v128, v64, v121
	ds_bpermute_b32 v129, v64, v122
	s_waitcnt lgkmcnt(5)
	v_add_f32_e32 v123, v123, v124
	s_waitcnt lgkmcnt(4)
	v_add_f32_e32 v119, v119, v125
	s_waitcnt lgkmcnt(3)
	v_add_f32_e32 v120, v120, v126
	ds_bpermute_b32 v124, v65, v123
	s_waitcnt lgkmcnt(3)
	v_add_f32_e32 v118, v118, v127
	ds_bpermute_b32 v125, v65, v119
	ds_bpermute_b32 v126, v65, v120
	s_waitcnt lgkmcnt(4)
	v_add_f32_e32 v121, v121, v128
	s_waitcnt lgkmcnt(3)
	v_add_f32_e32 v122, v122, v129
	ds_bpermute_b32 v127, v65, v118
	ds_bpermute_b32 v128, v65, v121
	ds_bpermute_b32 v129, v65, v122
	s_waitcnt lgkmcnt(5)
	v_add_f32_e32 v123, v123, v124
	s_waitcnt lgkmcnt(4)
	v_add_f32_e32 v119, v119, v125
	s_waitcnt lgkmcnt(3)
	v_add_f32_e32 v120, v120, v126
	ds_bpermute_b32 v124, v66, v123
	s_waitcnt lgkmcnt(3)
	v_add_f32_e32 v118, v118, v127
	ds_bpermute_b32 v125, v66, v119
	ds_bpermute_b32 v126, v66, v120
	s_waitcnt lgkmcnt(4)
	v_add_f32_e32 v121, v121, v128
	s_waitcnt lgkmcnt(3)
	v_add_f32_e32 v122, v122, v129
	ds_bpermute_b32 v127, v66, v118
	ds_bpermute_b32 v128, v66, v121
	ds_bpermute_b32 v129, v66, v122
	s_waitcnt lgkmcnt(5)
	v_add_f32_e32 v123, v123, v124
	s_waitcnt lgkmcnt(4)
	v_add_f32_e32 v119, v119, v125
	s_waitcnt lgkmcnt(3)
	v_add_f32_e32 v120, v120, v126
	ds_bpermute_b32 v124, v67, v123
	s_waitcnt lgkmcnt(3)
	v_add_f32_e32 v118, v118, v127
	ds_bpermute_b32 v125, v67, v119
	ds_bpermute_b32 v126, v67, v120
	s_waitcnt lgkmcnt(4)
	v_add_f32_e32 v121, v121, v128
	s_waitcnt lgkmcnt(3)
	v_add_f32_e32 v122, v122, v129
	ds_bpermute_b32 v127, v67, v118
	ds_bpermute_b32 v128, v67, v121
	ds_bpermute_b32 v129, v67, v122
	s_waitcnt lgkmcnt(5)
	v_add_f32_e32 v123, v123, v124
	s_waitcnt lgkmcnt(4)
	v_add_f32_e32 v119, v119, v125
	s_waitcnt lgkmcnt(3)
	v_add_f32_e32 v120, v120, v126
	v_fmamk_f32 v123, v123, 0x3b000000, v68
	s_waitcnt lgkmcnt(2)
	v_add_f32_e32 v118, v118, v127
	v_fmamk_f32 v119, v119, 0x3b000000, v68
	v_fmamk_f32 v120, v120, 0x3b000000, v68
	v_mul_f32_e32 v124, 0x4f800000, v123
	v_cmp_gt_f32_e64 s[4:5], s36, v123
	s_waitcnt lgkmcnt(1)
	v_add_f32_e32 v121, v121, v128
	s_waitcnt lgkmcnt(0)
	v_add_f32_e32 v122, v122, v129
	v_fmamk_f32 v118, v118, 0x3b000000, v68
	v_mul_f32_e32 v125, 0x4f800000, v119
	v_cmp_gt_f32_e32 vcc, s36, v119
	v_mul_f32_e32 v126, 0x4f800000, v120
	v_cmp_gt_f32_e64 s[0:1], s36, v120
	v_cndmask_b32_e64 v123, v123, v124, s[4:5]
	v_fmamk_f32 v121, v121, 0x3b000000, v68
	v_fmamk_f32 v122, v122, 0x3b000000, v68
	v_mul_f32_e32 v124, 0x4f800000, v118
	v_cmp_gt_f32_e64 s[6:7], s36, v118
	v_cndmask_b32_e32 v119, v119, v125, vcc
	v_cndmask_b32_e64 v120, v120, v126, s[0:1]
	v_sqrt_f32_e32 v127, v123
	v_mul_f32_e32 v125, 0x4f800000, v121
	v_cmp_gt_f32_e64 s[8:9], s36, v121
	v_mul_f32_e32 v126, 0x4f800000, v122
	v_cmp_gt_f32_e64 s[10:11], s36, v122
	v_cndmask_b32_e64 v118, v118, v124, s[6:7]
	v_sqrt_f32_e32 v124, v119
	v_sqrt_f32_e32 v128, v120
	v_cndmask_b32_e64 v121, v121, v125, s[8:9]
	v_cndmask_b32_e64 v122, v122, v126, s[10:11]
	v_sqrt_f32_e32 v125, v118
	v_sqrt_f32_e32 v126, v121
	v_sqrt_f32_e32 v129, v122
	v_add_u32_e32 v132, -1, v127
	v_add_u32_e32 v133, 1, v127
	v_add_u32_e32 v134, -1, v124
	v_add_u32_e32 v136, -1, v128
	v_fma_f32 v138, -v132, v127, v123
	v_add_u32_e32 v135, 1, v124
	v_add_u32_e32 v137, 1, v128
	v_fma_f32 v139, -v133, v127, v123
	v_add_u32_e32 v140, -1, v125
	v_fma_f32 v142, -v134, v124, v119
	v_fma_f32 v144, -v136, v128, v120
	v_cmp_ge_f32_e64 s[12:13], 0, v138
	v_add_u32_e32 v141, 1, v125
	v_fma_f32 v143, -v135, v124, v119
	v_fma_f32 v145, -v137, v128, v120
	v_add_u32_e32 v146, -1, v126
	v_add_u32_e32 v148, -1, v129
	v_cndmask_b32_e64 v127, v127, v132, s[12:13]
	v_fma_f32 v132, -v140, v125, v118
	v_cmp_ge_f32_e64 s[12:13], 0, v142
	v_cmp_ge_f32_e64 s[14:15], 0, v144
	v_cmp_lt_f32_e64 s[16:17], 0, v139
	v_add_u32_e32 v147, 1, v126
	v_add_u32_e32 v149, 1, v129
	v_fma_f32 v138, -v141, v125, v118
	v_cndmask_b32_e64 v124, v124, v134, s[12:13]
	v_cmp_lt_f32_e64 s[12:13], 0, v143
	v_cndmask_b32_e64 v128, v128, v136, s[14:15]
	v_cmp_lt_f32_e64 s[14:15], 0, v145
	v_fma_f32 v134, -v146, v126, v121
	v_fma_f32 v142, -v148, v129, v122
	v_cndmask_b32_e64 v127, v127, v133, s[16:17]
	v_cmp_ge_f32_e64 s[16:17], 0, v132
	v_fma_f32 v136, -v147, v126, v121
	v_fma_f32 v143, -v149, v129, v122
	v_cndmask_b32_e64 v125, v125, v140, s[16:17]
	v_cmp_lt_f32_e64 s[16:17], 0, v138
	v_cndmask_b32_e64 v124, v124, v135, s[12:13]
	v_cndmask_b32_e64 v128, v128, v137, s[14:15]
	v_cmp_ge_f32_e64 s[12:13], 0, v134
	v_cmp_ge_f32_e64 s[14:15], 0, v142
	v_mul_f32_e32 v132, 0x37800000, v127
	v_cndmask_b32_e64 v126, v126, v146, s[12:13]
	v_cmp_lt_f32_e64 s[12:13], 0, v136
	v_cndmask_b32_e64 v129, v129, v148, s[14:15]
	v_cmp_lt_f32_e64 s[14:15], 0, v143
	v_cndmask_b32_e64 v125, v125, v141, s[16:17]
	v_mul_f32_e32 v133, 0x37800000, v124
	v_mul_f32_e32 v134, 0x37800000, v128
	v_cndmask_b32_e64 v126, v126, v147, s[12:13]
	v_cndmask_b32_e64 v129, v129, v149, s[14:15]
	v_cndmask_b32_e64 v127, v127, v132, s[4:5]
	v_mul_f32_e32 v132, 0x37800000, v125
	v_cmp_class_f32_e64 s[4:5], v123, v69
	v_cndmask_b32_e32 v124, v124, v133, vcc
	v_cmp_class_f32_e32 vcc, v119, v69
	v_cndmask_b32_e64 v128, v128, v134, s[0:1]
	v_cmp_class_f32_e64 s[0:1], v120, v69
	v_mul_f32_e32 v133, 0x37800000, v126
	v_mul_f32_e32 v134, 0x37800000, v129
	v_cndmask_b32_e64 v123, v127, v123, s[4:5]
	v_cndmask_b32_e64 v125, v125, v132, s[6:7]
	v_cmp_class_f32_e64 s[4:5], v118, v69
	v_cndmask_b32_e32 v119, v124, v119, vcc
	v_cndmask_b32_e64 v120, v128, v120, s[0:1]
	v_cndmask_b32_e64 v124, v126, v133, s[8:9]
	v_cmp_class_f32_e32 vcc, v121, v69
	v_cndmask_b32_e64 v126, v129, v134, s[10:11]
	v_cmp_class_f32_e64 s[0:1], v122, v69
	v_div_scale_f32 v127, s[6:7], v123, v123, 1.0
	v_cndmask_b32_e64 v125, v125, v118, s[4:5]
	v_div_scale_f32 v118, s[4:5], v119, v119, 1.0
	v_div_scale_f32 v132, s[8:9], v120, v120, 1.0
	v_cndmask_b32_e32 v121, v124, v121, vcc
	v_cndmask_b32_e64 v122, v126, v122, s[0:1]
	v_rcp_f32_e32 v124, v127
	v_div_scale_f32 v126, s[0:1], v125, v125, 1.0
	v_rcp_f32_e32 v135, v118
	v_rcp_f32_e32 v136, v132
	v_div_scale_f32 v137, s[0:1], v121, v121, 1.0
	v_div_scale_f32 v139, s[0:1], v122, v122, 1.0
	v_rcp_f32_e32 v141, v126
	v_rcp_f32_e32 v142, v137
	v_rcp_f32_e32 v143, v139
	v_fma_f32 v144, -v127, v124, 1.0
	v_div_scale_f32 v128, s[6:7], 1.0, v123, 1.0
	v_fma_f32 v145, -v118, v135, 1.0
	v_fma_f32 v146, -v132, v136, 1.0
	v_fmac_f32_e32 v124, v144, v124
	v_fma_f32 v144, -v126, v141, 1.0
	v_div_scale_f32 v129, s[4:5], 1.0, v119, 1.0
	v_div_scale_f32 v134, s[10:11], 1.0, v125, 1.0
	v_fmac_f32_e32 v135, v145, v135
	v_fmac_f32_e32 v136, v146, v136
	v_fma_f32 v145, -v137, v142, 1.0
	v_fma_f32 v146, -v139, v143, 1.0
	v_mul_f32_e32 v147, v128, v124
	v_fmac_f32_e32 v141, v144, v141
	v_mul_f32_e32 v144, v129, v135
	v_fmac_f32_e32 v142, v145, v142
	v_fmac_f32_e32 v143, v146, v143
	v_fma_f32 v145, -v127, v147, v128
	v_mul_f32_e32 v146, v134, v141
	v_div_scale_f32 v133, s[8:9], 1.0, v120, 1.0
	v_fma_f32 v149, -v118, v144, v129
	v_fmac_f32_e32 v147, v145, v124
	v_fma_f32 v145, -v126, v146, v134
	v_div_scale_f32 v138, s[12:13], 1.0, v121, 1.0
	v_mul_f32_e32 v148, v133, v136
	v_fmac_f32_e32 v144, v149, v135
	v_fma_f32 v127, -v127, v147, v128
	v_fmac_f32_e32 v146, v145, v141
	s_mov_b64 vcc, s[6:7]
	v_fma_f32 v150, -v132, v148, v133
	v_mul_f32_e32 v151, v138, v142
	v_fma_f32 v128, -v118, v144, v129
	v_div_fmas_f32 v118, v127, v124, v147
	v_fma_f32 v124, -v126, v146, v134
	s_mov_b64 vcc, s[10:11]
	v_div_scale_f32 v140, s[0:1], 1.0, v122, 1.0
	v_fmac_f32_e32 v148, v150, v136
	v_fma_f32 v149, -v137, v151, v138
	v_div_fixup_f32 v118, v118, v123, 1.0
	v_div_fmas_f32 v123, v124, v141, v146
	s_mov_b64 vcc, s[4:5]
	v_mul_f32_e32 v152, v140, v143
	v_fma_f32 v129, -v132, v148, v133
	v_fmac_f32_e32 v151, v149, v142
	v_pk_mul_f32 v[42:43], v[42:43], v[118:119] op_sel_hi:[1,0]
	v_pk_mul_f32 v[44:45], v[44:45], v[118:119] op_sel_hi:[1,0]
	v_pk_mul_f32 v[46:47], v[46:47], v[118:119] op_sel_hi:[1,0]
	v_pk_mul_f32 v[48:49], v[48:49], v[118:119] op_sel_hi:[1,0]
	v_div_fixup_f32 v118, v123, v125, 1.0
	v_div_fmas_f32 v123, v128, v135, v144
	s_mov_b64 vcc, s[8:9]
	v_fma_f32 v150, -v139, v152, v140
	v_fma_f32 v126, -v137, v151, v138
	v_pk_mul_f32 v[48:49], v[4:5], v[48:49]
	v_pk_mul_f32 v[56:57], v[56:57], v[118:119] op_sel_hi:[1,0]
	v_pk_mul_f32 v[58:59], v[58:59], v[118:119] op_sel_hi:[1,0]
	v_pk_mul_f32 v[60:61], v[60:61], v[118:119] op_sel_hi:[1,0]
	v_pk_mul_f32 v[62:63], v[62:63], v[118:119] op_sel_hi:[1,0]
	v_div_fixup_f32 v118, v123, v119, 1.0
	v_div_fmas_f32 v119, v129, v136, v148
	s_mov_b64 vcc, s[12:13]
	v_fmac_f32_e32 v152, v150, v143
	v_pk_mul_f32 v[44:45], v[8:9], v[44:45]
	v_pk_mul_f32 v[42:43], v[6:7], v[42:43]
	v_pk_mul_f32 v[46:47], v[2:3], v[46:47]
	v_mul_f32_e32 v116, v48, v116
	v_mul_f32_e32 v117, v49, v117
	v_pk_mul_f32 v[48:49], v[2:3], v[60:61]
	v_pk_mul_f32 v[38:39], v[38:39], v[118:119] op_sel_hi:[1,0]
	v_div_fixup_f32 v60, v119, v120, 1.0
	v_div_fmas_f32 v61, v126, v142, v151
	v_fma_f32 v127, -v139, v152, v140
	v_mul_f32_e32 v110, v42, v110
	v_mul_f32_e32 v111, v43, v111
	v_mul_f32_e32 v112, v44, v112
	v_mul_f32_e32 v113, v45, v113
	v_mul_f32_e32 v114, v46, v114
	v_mul_f32_e32 v115, v47, v115
	v_pk_mul_f32 v[42:43], v[8:9], v[58:59]
	v_pk_mul_f32 v[44:45], v[6:7], v[56:57]
	v_pk_mul_f32 v[46:47], v[4:5], v[62:63]
	v_pk_mul_f32 v[56:57], v[34:35], v[118:119] op_sel_hi:[1,0]
	v_pk_mul_f32 v[58:59], v[36:37], v[118:119] op_sel_hi:[1,0]
	v_pk_mul_f32 v[40:41], v[40:41], v[118:119] op_sel_hi:[1,0]
	v_pk_mul_f32 v[38:39], v[2:3], v[38:39]
	v_pk_mul_f32 v[22:23], v[22:23], v[60:61] op_sel_hi:[1,0]
	s_mov_b64 vcc, s[0:1]
	v_cvt_pk_bf16_f32 v34, v110, v111
	v_cvt_pk_bf16_f32 v35, v112, v113
	v_cvt_pk_bf16_f32 v36, v114, v115
	v_cvt_pk_bf16_f32 v37, v116, v117
	v_mul_f32_e32 v62, v44, v102
	v_mul_f32_e32 v63, v45, v103
	v_mul_f32_e32 v102, v42, v104
	v_mul_f32_e32 v103, v43, v105
	v_mul_f32_e32 v104, v48, v106
	v_mul_f32_e32 v105, v49, v107
	v_mul_f32_e32 v106, v46, v108
	v_mul_f32_e32 v107, v47, v109
	v_pk_mul_f32 v[42:43], v[8:9], v[58:59]
	v_pk_mul_f32 v[44:45], v[6:7], v[56:57]
	v_pk_mul_f32 v[40:41], v[4:5], v[40:41]
	v_pk_mul_f32 v[46:47], v[18:19], v[60:61] op_sel_hi:[1,0]
	v_pk_mul_f32 v[48:49], v[20:21], v[60:61] op_sel_hi:[1,0]
	v_pk_mul_f32 v[24:25], v[24:25], v[60:61] op_sel_hi:[1,0]
	v_div_fixup_f32 v56, v61, v121, 1.0
	v_div_fmas_f32 v57, v127, v143, v152
	global_store_dwordx4 v130, v[34:37], s[28:29] nt
	v_cvt_pk_bf16_f32 v18, v62, v63
	v_cvt_pk_bf16_f32 v19, v102, v103
	v_cvt_pk_bf16_f32 v20, v104, v105
	v_mul_f32_e32 v39, v39, v99
	v_pk_mul_f32 v[22:23], v[2:3], v[22:23]
	v_cvt_pk_bf16_f32 v21, v106, v107
	v_mul_f32_e32 v44, v44, v94
	v_mul_f32_e32 v45, v45, v95
	v_mul_f32_e32 v42, v42, v96
	v_mul_f32_e32 v43, v43, v97
	v_mul_f32_e32 v58, v38, v98
	v_mul_f32_e32 v40, v40, v100
	v_mul_f32_e32 v41, v41, v101
	v_pk_mul_f32 v[34:35], v[8:9], v[48:49]
	v_pk_mul_f32 v[36:37], v[6:7], v[46:47]
	v_pk_mul_f32 v[24:25], v[4:5], v[24:25]
	v_pk_mul_f32 v[26:27], v[26:27], v[56:57] op_sel_hi:[1,0]
	v_pk_mul_f32 v[28:29], v[28:29], v[56:57] op_sel_hi:[1,0]
	v_pk_mul_f32 v[30:31], v[30:31], v[56:57] op_sel_hi:[1,0]
	v_pk_mul_f32 v[32:33], v[32:33], v[56:57] op_sel_hi:[1,0]
	v_div_fixup_f32 v38, v57, v122, 1.0
	global_store_dwordx4 v130, v[18:21], s[28:29] offset:1024 nt
	v_mul_f32_e32 v36, v36, v86
	v_mul_f32_e32 v37, v37, v87
	v_cvt_pk_bf16_f32 v18, v44, v45
	v_cvt_pk_bf16_f32 v19, v42, v43
	v_cvt_pk_bf16_f32 v20, v58, v39
	v_mul_f32_e32 v39, v22, v90
	v_cvt_pk_bf16_f32 v21, v40, v41
	v_mul_f32_e32 v34, v34, v88
	v_mul_f32_e32 v35, v35, v89
	v_mul_f32_e32 v40, v23, v91
	v_mul_f32_e32 v41, v24, v92
	v_mul_f32_e32 v42, v25, v93
	v_pk_mul_f32 v[22:23], v[8:9], v[28:29]
	v_pk_mul_f32 v[24:25], v[6:7], v[26:27]
	v_pk_mul_f32 v[26:27], v[4:5], v[32:33]
	v_pk_mul_f32 v[28:29], v[2:3], v[30:31]
	v_pk_mul_f32 v[30:31], v[10:11], v[38:39] op_sel_hi:[1,0]
	v_pk_mul_f32 v[32:33], v[12:13], v[38:39] op_sel_hi:[1,0]
	v_pk_mul_f32 v[14:15], v[14:15], v[38:39] op_sel_hi:[1,0]
	v_pk_mul_f32 v[16:17], v[16:17], v[38:39] op_sel_hi:[1,0]
	global_store_dwordx4 v130, v[18:21], s[28:29] offset:2048 nt
	v_cvt_pk_bf16_f32 v10, v36, v37
	v_cvt_pk_bf16_f32 v11, v34, v35
	v_cvt_pk_bf16_f32 v12, v39, v40
	v_cvt_pk_bf16_f32 v13, v41, v42
	v_mul_f32_e32 v24, v24, v78
	v_mul_f32_e32 v25, v25, v79
	v_mul_f32_e32 v22, v22, v80
	v_mul_f32_e32 v23, v23, v81
	v_mul_f32_e32 v28, v28, v82
	v_mul_f32_e32 v29, v29, v83
	v_mul_f32_e32 v26, v26, v84
	v_mul_f32_e32 v27, v27, v85
	v_pk_mul_f32 v[18:19], v[8:9], v[32:33]
	v_pk_mul_f32 v[20:21], v[6:7], v[30:31]
	v_pk_mul_f32 v[16:17], v[4:5], v[16:17]
	v_pk_mul_f32 v[14:15], v[2:3], v[14:15]
	global_store_dwordx4 v130, v[10:13], s[28:29] offset:3072 nt
	v_mul_f32_e32 v20, v20, v70
	v_mul_f32_e32 v21, v21, v71
	v_cvt_pk_bf16_f32 v10, v24, v25
	v_cvt_pk_bf16_f32 v11, v22, v23
	v_cvt_pk_bf16_f32 v12, v28, v29
	v_cvt_pk_bf16_f32 v13, v26, v27
	v_mul_f32_e32 v18, v18, v72
	v_mul_f32_e32 v19, v19, v73
	v_mul_f32_e32 v14, v14, v74
	v_mul_f32_e32 v15, v15, v75
	v_mul_f32_e32 v16, v16, v76
	v_mul_f32_e32 v17, v17, v77
	global_store_dwordx4 v[54:55], v[10:13], off nt
	s_nop 1
	v_cvt_pk_bf16_f32 v10, v20, v21
	v_cvt_pk_bf16_f32 v11, v18, v19
	v_cvt_pk_bf16_f32 v12, v14, v15
	v_cvt_pk_bf16_f32 v13, v16, v17
	global_store_dwordx4 v[54:55], v[10:13], off offset:1024 nt
	s_cbranch_scc1 .LBB0_1595
	s_cmpk_eq_u32 s99, 0x7771
	s_cbranch_scc0 .LBB0_1596
	s_movk_i32 s99, 0x7772
	v_writelane_b32 v254, s16, 27
	v_writelane_b32 v254, s21, 28
	v_writelane_b32 v254, s23, 29
	s_waitcnt vmcnt(0) lgkmcnt(0)
	s_barrier
	s_branch .Le22_gemm
